# peeled first K-iteration after each tile boundary in P2 and P7 (early A11 stage, relaxed vmcnt, SrcC=0 init)
# baseline (speedup 1.0000x reference)
; template <class Epi, class Sched, bool ALIGN_EPI = false, bool SP2 = false>
; __device__ __forceinline__ void gemm_phase(PG8_LAS unsigned char* lds, const Gemm g, const Sched& S, const Epi& E) {
;     ...
;         const char* nA = has_next ? (const char*)g.A + (size_t)nxt.pm * tstepA + (size_t)nxt.pn * apn : cA; const char* nB = has_next ? (const char*)g.Bt + (size_t)nxt.pn * tstepB : cB;
;     ...
;         for (int a = 0; a < 2; ++a)
; #pragma unroll
;             for (int b = 0; b < 2; ++b)
; #pragma unroll
;                 for (int m = 0; m < 4; ++m)
; #pragma unroll
;                     for (int n = 0; n < 2; ++n) acc[a][b][m][n] = (f32x4){0.f, 0.f, 0.f, 0.f};
.LBB0_604:
	s_ashr_i32 s13, s12, 31
	s_lshl_b64 s[14:15], s[12:13], 19
	s_add_u32 s14, s24, s14
	s_addc_u32 s15, s25, s15
	s_and_b64 s[16:17], s[2:3], exec
	s_cselect_b32 s13, s15, s39
	s_cselect_b32 s52, s14, s38
	s_ashr_i32 s11, s10, 31
	s_lshl_b64 s[16:17], s[10:11], 19
	s_add_u32 s16, s60, s16
	s_addc_u32 s17, s61, s17
	s_and_b64 s[42:43], s[2:3], exec
	s_cselect_b32 s11, s17, s41
	s_cselect_b32 s53, s16, s40
	s_add_u32 s38, s38, 0x40080
	s_addc_u32 s39, s39, 0
	s_add_u32 s54, s40, 0x100
	v_mov_b32_e32 v0, 0
	s_addc_u32 s55, s41, 0
	s_mov_b32 s56, -2
	s_cmp_lg_u32 s37, 1
	s_cbranch_scc1 .Lpeel_p7
	v_mov_b32_e32 v1, v0
	v_mov_b32_e32 v2, v0
	v_mov_b32_e32 v3, v0
	v_mov_b32_e32 v4, v0
	v_mov_b32_e32 v5, v0
	v_mov_b32_e32 v6, v0
	v_mov_b32_e32 v7, v0
	v_mov_b32_e32 v16, v0
	v_mov_b32_e32 v17, v0
	v_mov_b32_e32 v18, v0
	v_mov_b32_e32 v19, v0
	v_mov_b32_e32 v20, v0
	v_mov_b32_e32 v21, v0
	v_mov_b32_e32 v22, v0
	v_mov_b32_e32 v23, v0
	v_mov_b32_e32 v32, v0
	v_mov_b32_e32 v33, v0
	v_mov_b32_e32 v34, v0
	v_mov_b32_e32 v35, v0
	v_mov_b32_e32 v36, v0
	v_mov_b32_e32 v37, v0
	v_mov_b32_e32 v38, v0
	v_mov_b32_e32 v39, v0
	v_mov_b32_e32 v48, v0
	v_mov_b32_e32 v49, v0
	v_mov_b32_e32 v50, v0
	v_mov_b32_e32 v51, v0
	v_mov_b32_e32 v52, v0
	v_mov_b32_e32 v53, v0
	v_mov_b32_e32 v54, v0
	v_mov_b32_e32 v55, v0
	v_mov_b32_e32 v8, v0
	v_mov_b32_e32 v9, v0
	v_mov_b32_e32 v10, v0
	v_mov_b32_e32 v11, v0
	v_mov_b32_e32 v12, v0
	v_mov_b32_e32 v13, v0
	v_mov_b32_e32 v14, v0
	v_mov_b32_e32 v15, v0
	v_mov_b32_e32 v24, v0
	v_mov_b32_e32 v25, v0
	v_mov_b32_e32 v26, v0
	v_mov_b32_e32 v27, v0
	v_mov_b32_e32 v28, v0
	v_mov_b32_e32 v29, v0
	v_mov_b32_e32 v30, v0
	v_mov_b32_e32 v31, v0
	v_mov_b32_e32 v40, v0
	v_mov_b32_e32 v41, v0
	v_mov_b32_e32 v42, v0
	v_mov_b32_e32 v43, v0
	v_mov_b32_e32 v44, v0
	v_mov_b32_e32 v45, v0
	v_mov_b32_e32 v46, v0
	v_mov_b32_e32 v47, v0
	v_mov_b32_e32 v56, v0
	v_mov_b32_e32 v57, v0
	v_mov_b32_e32 v58, v0
	v_mov_b32_e32 v59, v0
	v_mov_b32_e32 v60, v0
	v_mov_b32_e32 v61, v0
	v_mov_b32_e32 v62, v0
	v_mov_b32_e32 v63, v0
	v_mov_b32_e32 v64, v0
	v_mov_b32_e32 v65, v0
	v_mov_b32_e32 v66, v0
	v_mov_b32_e32 v67, v0
	v_mov_b32_e32 v68, v0
	v_mov_b32_e32 v69, v0
	v_mov_b32_e32 v70, v0
	v_mov_b32_e32 v71, v0
	v_mov_b32_e32 v80, v0
	v_mov_b32_e32 v81, v0
	v_mov_b32_e32 v82, v0
	v_mov_b32_e32 v83, v0
	v_mov_b32_e32 v84, v0
	v_mov_b32_e32 v85, v0
	v_mov_b32_e32 v86, v0
	v_mov_b32_e32 v87, v0
	v_mov_b32_e32 v96, v0
	v_mov_b32_e32 v97, v0
	v_mov_b32_e32 v98, v0
	v_mov_b32_e32 v99, v0
	v_mov_b32_e32 v100, v0
	v_mov_b32_e32 v101, v0
	v_mov_b32_e32 v102, v0
	v_mov_b32_e32 v103, v0
	v_mov_b32_e32 v112, v0
	v_mov_b32_e32 v113, v0
	v_mov_b32_e32 v114, v0
	v_mov_b32_e32 v115, v0
	v_mov_b32_e32 v116, v0
	v_mov_b32_e32 v117, v0
	v_mov_b32_e32 v118, v0
	v_mov_b32_e32 v119, v0
	v_mov_b32_e32 v72, v0
	v_mov_b32_e32 v73, v0
	v_mov_b32_e32 v74, v0
	v_mov_b32_e32 v75, v0
	v_mov_b32_e32 v76, v0
	v_mov_b32_e32 v77, v0
	v_mov_b32_e32 v78, v0
	v_mov_b32_e32 v79, v0
	v_mov_b32_e32 v88, v0
	v_mov_b32_e32 v89, v0
	v_mov_b32_e32 v90, v0
	v_mov_b32_e32 v91, v0
	v_mov_b32_e32 v92, v0
	v_mov_b32_e32 v93, v0
	v_mov_b32_e32 v94, v0
	v_mov_b32_e32 v95, v0
	v_mov_b32_e32 v104, v0
	v_mov_b32_e32 v105, v0
	v_mov_b32_e32 v106, v0
	v_mov_b32_e32 v107, v0
	v_mov_b32_e32 v108, v0
	v_mov_b32_e32 v109, v0
	v_mov_b32_e32 v110, v0
	v_mov_b32_e32 v111, v0
	v_mov_b32_e32 v120, v0
	v_mov_b32_e32 v121, v0
	v_mov_b32_e32 v122, v0
	v_mov_b32_e32 v123, v0
	v_mov_b32_e32 v124, v0
	v_mov_b32_e32 v125, v0
	v_mov_b32_e32 v126, v0
	v_mov_b32_e32 v127, v0

; __device__ __forceinline__ unsigned cvt_pk_bf16(float lo, float hi) { unsigned r; asm volatile("v_cvt_pk_bf16_f32 %0, %1, %2" : "=v"(r) : "v"(lo), "v"(hi)); return r; }
; __device__ __forceinline__ float sigm(float x) { return __builtin_amdgcn_rcpf(1.0f + __builtin_amdgcn_exp2f(-1.4426950408889634f * x)); }
; #define PG8_STAGE(bufoff, gbase, voff) do { _Pragma("unroll") for (int _i = 0; _i < 2; ++_i) \
;         __builtin_amdgcn_global_load_lds((const unsigned*)((const char*)(gbase) + (voff)[_i]), (PG8_LAS unsigned*)(lds + (bufoff) + ldsw + _i * 8192), 16, 0, 0); } while (0)
; #define PG8_LDA(dst, b, h) do { _Pragma("unroll") for (int m = 0; m < 4; ++m) _Pragma("unroll") for (int k = 0; k < 2; ++k) dst[m][k] = *(const PG8_LAS bf16x8*)(lds + PG8_SA(b, h) + aoff + m * 2048 + k * 1024); } while (0)
; #define PG8_LDB(dst, b, h) do { _Pragma("unroll") for (int n = 0; n < 2; ++n) _Pragma("unroll") for (int k = 0; k < 2; ++k) dst[n][k] = *(const PG8_LAS bf16x8*)(lds + PG8_SB(b, h) + boff + n * 2048 + k * 1024); } while (0)
;     __device__ __forceinline__ void operator()(const f32x4 (&acc)[2][2][4][2], const Unit& u, int wr, int wc, int fr, int fq) const {
;         const int row0 = u.pm * BM + wr * 64 + fr, col0 = u.pn * 128 + wc * 32 + 8 * fq;
; #pragma unroll
;         for (int ai = 0; ai < 2; ++ai)
; #pragma unroll
;             for (int m = 0; m < 4; ++m) { bf16_t* rowp = out + (size_t)(row0 + ai * HALF + m * 16) * 2816 + col0;
;                 const f32x4 g0 = acc[ai][0][m][0], g1 = acc[ai][0][m][1], u0 = acc[ai][1][m][0], u1 = acc[ai][1][m][1];
;                 u32x4 w;
;                 w.x = cvt_pk_bf16(g0[0] * sigm(g0[0]) * u0[0], g0[1] * sigm(g0[1]) * u0[1]);
;                 w.y = cvt_pk_bf16(g0[2] * sigm(g0[2]) * u0[2], g0[3] * sigm(g0[3]) * u0[3]);
;                 w.z = cvt_pk_bf16(g1[0] * sigm(g1[0]) * u1[0], g1[1] * sigm(g1[1]) * u1[1]);
;                 w.w = cvt_pk_bf16(g1[2] * sigm(g1[2]) * u1[2], g1[3] * sigm(g1[3]) * u1[3]);
;                 __builtin_nontemporal_store(w, (u32x4*)rowp); }
; template <class Epi, class Sched, bool ALIGN_EPI = false, bool SP2 = false>
; __device__ __forceinline__ void gemm_phase(PG8_LAS unsigned char* lds, const Gemm g, const Sched& S, const Epi& E) {
;     ...
;             PG8_LDB(B0, 0, 0); PG8_LDB(B1, 0, 1); PG8_SCHED; PG8_LDA(At, 0, 0); PG8_STAGE(PG8_SA(1, 1), a1 + hstepA, voffA);
.LBB0_608:
	s_add_u32 s100, s52, 0x40080
	s_addc_u32 s101, s13, 0
	v_lshl_add_u64 v[216:217], s[100:101], 0, v[136:137]
	s_add_i32 m0, s29, 0xc000
	v_lshl_add_u64 v[218:219], s[100:101], 0, v[138:139]
	global_load_lds_dwordx4 v[216:217], off
	s_add_i32 m0, s29, 0xe000
	s_nop 0
	global_load_lds_dwordx4 v[218:219], off
	v_mul_f32_e32 v155, 0xbfb8aa3b, v124
	v_exp_f32_e32 v155, v155
	v_mul_f32_e32 v158, 0xbfb8aa3b, v125
	v_exp_f32_e32 v158, v158
	v_lshl_or_b32 v146, s51, 7, v150
	v_add_f32_e32 v155, 1.0, v155
	v_rcp_f32_e32 v155, v155
	v_add_f32_e32 v158, 1.0, v158
	v_rcp_f32_e32 v158, v158
	v_lshl_add_u32 v154, s36, 8, v148
	v_mul_f32_e32 v124, v124, v155
	v_mul_f32_e32 v116, v124, v116
	v_mul_f32_e32 v124, v125, v158
	v_mul_f32_e32 v125, 0xbfb8aa3b, v126
	v_exp_f32_e32 v125, v125
	v_mul_f32_e32 v155, 0xbfb8aa3b, v127
	v_exp_f32_e32 v155, v155
	v_mul_f32_e32 v117, v124, v117
	v_add_f32_e32 v124, 1.0, v125
	v_rcp_f32_e32 v124, v124
	v_add_f32_e32 v125, 1.0, v155
	v_rcp_f32_e32 v125, v125
	v_cvt_pk_bf16_f32 v116, v116, v117
	v_mul_f32_e32 v117, v126, v124
	v_mul_f32_e32 v124, 0xbfb8aa3b, v120
	v_exp_f32_e32 v124, v124
	v_mul_f32_e32 v117, v117, v118
	v_mul_f32_e32 v118, v127, v125
	v_mul_f32_e32 v125, 0xbfb8aa3b, v121
	v_exp_f32_e32 v125, v125
	v_mul_f32_e32 v118, v118, v119
	v_add_f32_e32 v119, 1.0, v124
	v_rcp_f32_e32 v119, v119
	v_add_f32_e32 v124, 1.0, v125
	v_rcp_f32_e32 v124, v124
	v_cvt_pk_bf16_f32 v117, v117, v118
	v_mul_f32_e32 v118, v120, v119
	v_mul_f32_e32 v119, 0xbfb8aa3b, v122
	v_exp_f32_e32 v119, v119
	v_mul_f32_e32 v120, 0xbfb8aa3b, v123
	v_exp_f32_e32 v120, v120
	v_mul_f32_e32 v112, v118, v112
	v_mul_f32_e32 v118, v121, v124
	v_mul_f32_e32 v113, v118, v113
	v_add_f32_e32 v118, 1.0, v119
	v_rcp_f32_e32 v119, v118
	v_add_f32_e32 v118, 1.0, v120
	v_rcp_f32_e32 v120, v118
	v_cvt_pk_bf16_f32 v118, v112, v113
	v_mul_f32_e32 v112, v122, v119
	v_mul_f32_e32 v112, v112, v114
	v_mul_f32_e32 v113, v123, v120
	v_mul_f32_e32 v113, v113, v115
	v_cvt_pk_bf16_f32 v119, v112, v113
	v_mul_f32_e32 v113, 0xbfb8aa3b, v108
	v_exp_f32_e32 v114, v113
	v_mul_f32_e32 v113, 0xbfb8aa3b, v109
	v_exp_f32_e32 v115, v113
	v_ashrrev_i32_e32 v147, 31, v146
	v_add_f32_e32 v114, 1.0, v114
	v_rcp_f32_e32 v114, v114
	v_add_f32_e32 v115, 1.0, v115
	v_rcp_f32_e32 v115, v115
	v_mov_b64_e32 v[144:145], s[18:19]
	v_mul_f32_e32 v108, v108, v114
	v_mul_f32_e32 v100, v108, v100
	v_mul_f32_e32 v108, v109, v115
	v_mul_f32_e32 v109, 0xbfb8aa3b, v110
	v_exp_f32_e32 v109, v109
	v_mul_f32_e32 v114, 0xbfb8aa3b, v111
	v_exp_f32_e32 v114, v114
	v_mul_f32_e32 v101, v108, v101
	v_add_f32_e32 v108, 1.0, v109
	v_rcp_f32_e32 v108, v108
	v_mad_i64_i32 v[156:157], s[38:39], v154, s50, v[144:145]
	v_lshlrev_b64 v[146:147], 1, v[146:147]
	v_lshl_add_u64 v[156:157], v[156:157], 0, v[146:147]
	v_add_f32_e32 v109, 1.0, v114
	global_store_dwordx4 v[156:157], v[116:119], off nt
	v_rcp_f32_e32 v109, v109
	v_cvt_pk_bf16_f32 v100, v100, v101
	v_mul_f32_e32 v101, v110, v108
	v_mul_f32_e32 v108, 0xbfb8aa3b, v104
	v_exp_f32_e32 v108, v108
	v_mul_f32_e32 v101, v101, v102
	v_mul_f32_e32 v102, v111, v109
	v_mul_f32_e32 v109, 0xbfb8aa3b, v105
	v_exp_f32_e32 v109, v109
	v_mul_f32_e32 v102, v102, v103
	v_add_f32_e32 v103, 1.0, v108
	v_rcp_f32_e32 v103, v103
	v_add_f32_e32 v108, 1.0, v109
	v_rcp_f32_e32 v108, v108
	v_cvt_pk_bf16_f32 v101, v101, v102
	v_mul_f32_e32 v102, v104, v103
	v_mul_f32_e32 v103, 0xbfb8aa3b, v106
	v_exp_f32_e32 v103, v103
	v_mul_f32_e32 v104, 0xbfb8aa3b, v107
	v_exp_f32_e32 v104, v104
	v_mul_f32_e32 v96, v102, v96
	v_mul_f32_e32 v102, v105, v108
	v_mul_f32_e32 v97, v102, v97
	v_add_f32_e32 v102, 1.0, v103
	v_rcp_f32_e32 v103, v102
	v_add_f32_e32 v102, 1.0, v104
	v_rcp_f32_e32 v104, v102
	v_cvt_pk_bf16_f32 v102, v96, v97
	v_mul_f32_e32 v96, v106, v103
	v_mul_f32_e32 v96, v96, v98
	v_mul_f32_e32 v97, v107, v104
	v_mul_f32_e32 v97, v97, v99
	v_cvt_pk_bf16_f32 v103, v96, v97
	v_mul_f32_e32 v97, 0xbfb8aa3b, v92
	v_exp_f32_e32 v98, v97
	v_mul_f32_e32 v97, 0xbfb8aa3b, v93
	v_exp_f32_e32 v99, v97
	v_or_b32_e32 v112, 16, v154
	v_add_f32_e32 v98, 1.0, v98
	v_rcp_f32_e32 v98, v98
	v_add_f32_e32 v99, 1.0, v99
	v_rcp_f32_e32 v99, v99
	v_mad_i64_i32 v[112:113], s[38:39], v112, s50, v[144:145]
	v_mul_f32_e32 v92, v92, v98
	v_mul_f32_e32 v84, v92, v84
	v_mul_f32_e32 v92, v93, v99
	v_mul_f32_e32 v93, 0xbfb8aa3b, v94
	v_exp_f32_e32 v93, v93
	v_mul_f32_e32 v98, 0xbfb8aa3b, v95
	v_exp_f32_e32 v98, v98
	v_mul_f32_e32 v85, v92, v85
	v_add_f32_e32 v92, 1.0, v93
	v_rcp_f32_e32 v92, v92
	v_lshl_add_u64 v[112:113], v[112:113], 0, v[146:147]
	v_add_f32_e32 v93, 1.0, v98
	global_store_dwordx4 v[112:113], v[100:103], off nt
	v_rcp_f32_e32 v93, v93
	v_cvt_pk_bf16_f32 v84, v84, v85
	v_mul_f32_e32 v85, v94, v92
	v_mul_f32_e32 v92, 0xbfb8aa3b, v88
	v_exp_f32_e32 v92, v92
	v_mul_f32_e32 v85, v85, v86
	v_mul_f32_e32 v86, v95, v93
	v_mul_f32_e32 v93, 0xbfb8aa3b, v89
	v_exp_f32_e32 v93, v93
	v_mul_f32_e32 v86, v86, v87
	v_add_f32_e32 v87, 1.0, v92
	v_rcp_f32_e32 v87, v87
	v_add_f32_e32 v92, 1.0, v93
	v_rcp_f32_e32 v92, v92
	v_cvt_pk_bf16_f32 v85, v85, v86
	v_mul_f32_e32 v86, v88, v87
	v_mul_f32_e32 v87, 0xbfb8aa3b, v90
	v_exp_f32_e32 v87, v87
	v_mul_f32_e32 v88, 0xbfb8aa3b, v91
	v_exp_f32_e32 v88, v88
	v_mul_f32_e32 v80, v86, v80
	v_mul_f32_e32 v86, v89, v92
	v_mul_f32_e32 v81, v86, v81
	v_add_f32_e32 v86, 1.0, v87
	v_rcp_f32_e32 v87, v86
	v_add_f32_e32 v86, 1.0, v88
	v_rcp_f32_e32 v88, v86
	v_cvt_pk_bf16_f32 v86, v80, v81
	v_mul_f32_e32 v80, v90, v87
	v_mul_f32_e32 v80, v80, v82
	v_mul_f32_e32 v81, v91, v88
	v_mul_f32_e32 v81, v81, v83
	v_cvt_pk_bf16_f32 v87, v80, v81
	v_mul_f32_e32 v81, 0xbfb8aa3b, v76
; __device__ __forceinline__ unsigned cvt_pk_bf16(float lo, float hi) { unsigned r; asm volatile("v_cvt_pk_bf16_f32 %0, %1, %2" : "=v"(r) : "v"(lo), "v"(hi)); return r; }
; __device__ __forceinline__ float sigm(float x) { return __builtin_amdgcn_rcpf(1.0f + __builtin_amdgcn_exp2f(-1.4426950408889634f * x)); }
;     __device__ __forceinline__ void operator()(const f32x4 (&acc)[2][2][4][2], const Unit& u, int wr, int wc, int fr, int fq) const {
;         const int row0 = u.pm * BM + wr * 64 + fr, col0 = u.pn * 128 + wc * 32 + 8 * fq;
; #pragma unroll
;         for (int ai = 0; ai < 2; ++ai)
; #pragma unroll
;             for (int m = 0; m < 4; ++m) { bf16_t* rowp = out + (size_t)(row0 + ai * HALF + m * 16) * 2816 + col0;
;                 const f32x4 g0 = acc[ai][0][m][0], g1 = acc[ai][0][m][1], u0 = acc[ai][1][m][0], u1 = acc[ai][1][m][1];
;                 u32x4 w;
;                 w.x = cvt_pk_bf16(g0[0] * sigm(g0[0]) * u0[0], g0[1] * sigm(g0[1]) * u0[1]);
;                 w.y = cvt_pk_bf16(g0[2] * sigm(g0[2]) * u0[2], g0[3] * sigm(g0[3]) * u0[3]);
;                 w.z = cvt_pk_bf16(g1[0] * sigm(g1[0]) * u1[0], g1[1] * sigm(g1[1]) * u1[1]);
;                 w.w = cvt_pk_bf16(g1[2] * sigm(g1[2]) * u1[2], g1[3] * sigm(g1[3]) * u1[3]);
;                 __builtin_nontemporal_store(w, (u32x4*)rowp); }
	v_exp_f32_e32 v82, v81
	v_mul_f32_e32 v81, 0xbfb8aa3b, v77
	v_exp_f32_e32 v83, v81
	v_or_b32_e32 v96, 32, v154
	v_add_f32_e32 v82, 1.0, v82
	v_rcp_f32_e32 v82, v82
	v_add_f32_e32 v83, 1.0, v83
	v_rcp_f32_e32 v83, v83
	v_mad_i64_i32 v[96:97], s[38:39], v96, s50, v[144:145]
	v_mul_f32_e32 v76, v76, v82
	v_mul_f32_e32 v68, v76, v68
	v_mul_f32_e32 v76, v77, v83
	v_mul_f32_e32 v77, 0xbfb8aa3b, v78
	v_exp_f32_e32 v77, v77
	v_mul_f32_e32 v82, 0xbfb8aa3b, v79
	v_exp_f32_e32 v82, v82
	v_mul_f32_e32 v69, v76, v69
	v_add_f32_e32 v76, 1.0, v77
	v_rcp_f32_e32 v76, v76
	v_lshl_add_u64 v[96:97], v[96:97], 0, v[146:147]
	v_add_f32_e32 v77, 1.0, v82
	global_store_dwordx4 v[96:97], v[84:87], off nt
	v_rcp_f32_e32 v77, v77
	v_cvt_pk_bf16_f32 v68, v68, v69
	v_mul_f32_e32 v69, v78, v76
	v_mul_f32_e32 v76, 0xbfb8aa3b, v72
	v_exp_f32_e32 v76, v76
	v_mul_f32_e32 v69, v69, v70
	v_mul_f32_e32 v70, v79, v77
	v_mul_f32_e32 v77, 0xbfb8aa3b, v73
	v_exp_f32_e32 v77, v77
	v_mul_f32_e32 v70, v70, v71
	v_add_f32_e32 v71, 1.0, v76
	v_rcp_f32_e32 v71, v71
	v_add_f32_e32 v76, 1.0, v77
	v_rcp_f32_e32 v76, v76
	v_cvt_pk_bf16_f32 v69, v69, v70
	v_mul_f32_e32 v70, v72, v71
	v_mul_f32_e32 v71, 0xbfb8aa3b, v74
	v_exp_f32_e32 v71, v71
	v_mul_f32_e32 v72, 0xbfb8aa3b, v75
	v_exp_f32_e32 v72, v72
	v_mul_f32_e32 v64, v70, v64
	v_mul_f32_e32 v70, v73, v76
	v_mul_f32_e32 v65, v70, v65
	v_add_f32_e32 v70, 1.0, v71
	v_rcp_f32_e32 v71, v70
	v_add_f32_e32 v70, 1.0, v72
	v_rcp_f32_e32 v72, v70
	v_cvt_pk_bf16_f32 v70, v64, v65
	v_mul_f32_e32 v64, v74, v71
	v_mul_f32_e32 v64, v64, v66
	v_mul_f32_e32 v65, v75, v72
	v_mul_f32_e32 v65, v65, v67
	v_cvt_pk_bf16_f32 v71, v64, v65
	v_mul_f32_e32 v65, 0xbfb8aa3b, v60
	v_exp_f32_e32 v66, v65
	v_mul_f32_e32 v65, 0xbfb8aa3b, v61
	v_exp_f32_e32 v67, v65
	v_or_b32_e32 v80, 48, v154
	v_add_f32_e32 v66, 1.0, v66
	v_rcp_f32_e32 v66, v66
	v_add_f32_e32 v67, 1.0, v67
	v_rcp_f32_e32 v67, v67
	v_mad_i64_i32 v[80:81], s[38:39], v80, s50, v[144:145]
	v_mul_f32_e32 v60, v60, v66
	v_mul_f32_e32 v52, v60, v52
	v_mul_f32_e32 v60, v61, v67
	v_mul_f32_e32 v61, 0xbfb8aa3b, v62
	v_exp_f32_e32 v61, v61
	v_mul_f32_e32 v66, 0xbfb8aa3b, v63
	v_exp_f32_e32 v66, v66
	v_mul_f32_e32 v53, v60, v53
	v_add_f32_e32 v60, 1.0, v61
	v_rcp_f32_e32 v60, v60
	v_lshl_add_u64 v[80:81], v[80:81], 0, v[146:147]
	v_add_f32_e32 v61, 1.0, v66
	global_store_dwordx4 v[80:81], v[68:71], off nt
	v_rcp_f32_e32 v61, v61
	v_cvt_pk_bf16_f32 v52, v52, v53
	v_mul_f32_e32 v53, v62, v60
	v_mul_f32_e32 v60, 0xbfb8aa3b, v56
	v_exp_f32_e32 v60, v60
	v_mul_f32_e32 v53, v53, v54
	v_mul_f32_e32 v54, v63, v61
	v_mul_f32_e32 v61, 0xbfb8aa3b, v57
	v_exp_f32_e32 v61, v61
	v_mul_f32_e32 v54, v54, v55
	v_add_f32_e32 v55, 1.0, v60
	v_rcp_f32_e32 v55, v55
	v_add_f32_e32 v60, 1.0, v61
	v_rcp_f32_e32 v60, v60
	v_cvt_pk_bf16_f32 v53, v53, v54
	v_mul_f32_e32 v54, v56, v55
	v_mul_f32_e32 v55, 0xbfb8aa3b, v58
	v_exp_f32_e32 v55, v55
	v_mul_f32_e32 v56, 0xbfb8aa3b, v59
	v_exp_f32_e32 v56, v56
	v_mul_f32_e32 v48, v54, v48
	v_mul_f32_e32 v54, v57, v60
	v_mul_f32_e32 v49, v54, v49
	v_add_f32_e32 v54, 1.0, v55
	v_rcp_f32_e32 v55, v54
	v_add_f32_e32 v54, 1.0, v56
	v_rcp_f32_e32 v56, v54
	v_cvt_pk_bf16_f32 v54, v48, v49
	v_mul_f32_e32 v48, v58, v55
	v_mul_f32_e32 v48, v48, v50
	v_mul_f32_e32 v49, v59, v56
	v_mul_f32_e32 v49, v49, v51
	v_cvt_pk_bf16_f32 v55, v48, v49
	v_mul_f32_e32 v49, 0xbfb8aa3b, v44
	v_exp_f32_e32 v50, v49
	v_mul_f32_e32 v49, 0xbfb8aa3b, v45
	v_exp_f32_e32 v51, v49
	v_add_u32_e32 v64, 0x80, v154
	v_add_f32_e32 v50, 1.0, v50
	v_rcp_f32_e32 v50, v50
	v_add_f32_e32 v51, 1.0, v51
	v_rcp_f32_e32 v51, v51
	v_mad_i64_i32 v[64:65], s[38:39], v64, s50, v[144:145]
	v_mul_f32_e32 v44, v44, v50
	v_mul_f32_e32 v36, v44, v36
	v_mul_f32_e32 v44, v45, v51
	v_mul_f32_e32 v45, 0xbfb8aa3b, v46
	v_exp_f32_e32 v45, v45
	v_mul_f32_e32 v50, 0xbfb8aa3b, v47
	v_exp_f32_e32 v50, v50
	v_mul_f32_e32 v37, v44, v37
	v_add_f32_e32 v44, 1.0, v45
	v_rcp_f32_e32 v44, v44
	v_lshl_add_u64 v[64:65], v[64:65], 0, v[146:147]
	v_add_f32_e32 v45, 1.0, v50
	global_store_dwordx4 v[64:65], v[52:55], off nt
	v_rcp_f32_e32 v45, v45
	v_cvt_pk_bf16_f32 v36, v36, v37
	v_mul_f32_e32 v37, v46, v44
	v_mul_f32_e32 v44, 0xbfb8aa3b, v40
	v_exp_f32_e32 v44, v44
	v_mul_f32_e32 v37, v37, v38
	v_mul_f32_e32 v38, v47, v45
	v_mul_f32_e32 v45, 0xbfb8aa3b, v41
	v_exp_f32_e32 v45, v45
	v_mul_f32_e32 v38, v38, v39
	v_add_f32_e32 v39, 1.0, v44
	v_rcp_f32_e32 v39, v39
	v_add_f32_e32 v44, 1.0, v45
	v_rcp_f32_e32 v44, v44
	v_cvt_pk_bf16_f32 v37, v37, v38
	v_mul_f32_e32 v38, v40, v39
	v_mul_f32_e32 v39, 0xbfb8aa3b, v42
	v_exp_f32_e32 v39, v39
	v_mul_f32_e32 v40, 0xbfb8aa3b, v43
	v_exp_f32_e32 v40, v40
	v_mul_f32_e32 v32, v38, v32
	v_mul_f32_e32 v38, v41, v44
	v_mul_f32_e32 v33, v38, v33
	v_add_f32_e32 v38, 1.0, v39
	v_rcp_f32_e32 v39, v38
	v_add_f32_e32 v38, 1.0, v40
	v_rcp_f32_e32 v40, v38
	v_cvt_pk_bf16_f32 v38, v32, v33
	v_mul_f32_e32 v32, v42, v39
	v_mul_f32_e32 v32, v32, v34
	v_mul_f32_e32 v33, v43, v40
	v_mul_f32_e32 v33, v33, v35
	v_cvt_pk_bf16_f32 v39, v32, v33
	v_mul_f32_e32 v33, 0xbfb8aa3b, v28
	v_exp_f32_e32 v34, v33
	v_mul_f32_e32 v33, 0xbfb8aa3b, v29
	v_exp_f32_e32 v35, v33
	v_add_u32_e32 v48, 0x90, v154
	v_add_f32_e32 v34, 1.0, v34
	v_rcp_f32_e32 v34, v34
	v_add_f32_e32 v35, 1.0, v35
	v_rcp_f32_e32 v35, v35
	v_mad_i64_i32 v[48:49], s[38:39], v48, s50, v[144:145]
	v_mul_f32_e32 v28, v28, v34
	v_mul_f32_e32 v20, v28, v20
	v_mul_f32_e32 v28, v29, v35
	v_mul_f32_e32 v29, 0xbfb8aa3b, v30
	v_exp_f32_e32 v29, v29
	v_mul_f32_e32 v34, 0xbfb8aa3b, v31
	v_exp_f32_e32 v34, v34
	v_mul_f32_e32 v21, v28, v21
	v_add_f32_e32 v28, 1.0, v29
	v_rcp_f32_e32 v28, v28
; __device__ __forceinline__ unsigned cvt_pk_bf16(float lo, float hi) { unsigned r; asm volatile("v_cvt_pk_bf16_f32 %0, %1, %2" : "=v"(r) : "v"(lo), "v"(hi)); return r; }
; __device__ __forceinline__ float sigm(float x) { return __builtin_amdgcn_rcpf(1.0f + __builtin_amdgcn_exp2f(-1.4426950408889634f * x)); }
; #define PG8_STAGE(bufoff, gbase, voff) do { _Pragma("unroll") for (int _i = 0; _i < 2; ++_i) \
;         __builtin_amdgcn_global_load_lds((const unsigned*)((const char*)(gbase) + (voff)[_i]), (PG8_LAS unsigned*)(lds + (bufoff) + ldsw + _i * 8192), 16, 0, 0); } while (0)
; #define PG8_LDA(dst, b, h) do { _Pragma("unroll") for (int m = 0; m < 4; ++m) _Pragma("unroll") for (int k = 0; k < 2; ++k) dst[m][k] = *(const PG8_LAS bf16x8*)(lds + PG8_SA(b, h) + aoff + m * 2048 + k * 1024); } while (0)
; #define PG8_LDB(dst, b, h) do { _Pragma("unroll") for (int n = 0; n < 2; ++n) _Pragma("unroll") for (int k = 0; k < 2; ++k) dst[n][k] = *(const PG8_LAS bf16x8*)(lds + PG8_SB(b, h) + boff + n * 2048 + k * 1024); } while (0)
; #define PG8_BAR __builtin_amdgcn_s_barrier()
;     __device__ __forceinline__ void operator()(const f32x4 (&acc)[2][2][4][2], const Unit& u, int wr, int wc, int fr, int fq) const {
;     ...
;             for (int m = 0; m < 4; ++m) { bf16_t* rowp = out + (size_t)(row0 + ai * HALF + m * 16) * 2816 + col0;
;                 const f32x4 g0 = acc[ai][0][m][0], g1 = acc[ai][0][m][1], u0 = acc[ai][1][m][0], u1 = acc[ai][1][m][1];
;                 u32x4 w;
;                 w.x = cvt_pk_bf16(g0[0] * sigm(g0[0]) * u0[0], g0[1] * sigm(g0[1]) * u0[1]);
;                 w.y = cvt_pk_bf16(g0[2] * sigm(g0[2]) * u0[2], g0[3] * sigm(g0[3]) * u0[3]);
;                 w.z = cvt_pk_bf16(g1[0] * sigm(g1[0]) * u1[0], g1[1] * sigm(g1[1]) * u1[1]);
;                 w.w = cvt_pk_bf16(g1[2] * sigm(g1[2]) * u1[2], g1[3] * sigm(g1[3]) * u1[3]);
;                 __builtin_nontemporal_store(w, (u32x4*)rowp); }
; template <class Epi, class Sched, bool ALIGN_EPI = false, bool SP2 = false>
; __device__ __forceinline__ void gemm_phase(PG8_LAS unsigned char* lds, const Gemm g, const Sched& S, const Epi& E) {
;     ...
;             PG8_LDB(B0, 0, 0); PG8_LDB(B1, 0, 1); PG8_SCHED; PG8_LDA(At, 0, 0); PG8_STAGE(PG8_SA(1, 1), a1 + hstepA, voffA);
;             PG8_WAIT_V(8); PG8_WAIT_L(0); PG8_BAR; PG8_MMA(0, 0, At, B0); PG8_MMA(0, 1, At, B1); PG8_BAR; PG8_SCHED;
	v_lshl_add_u64 v[48:49], v[48:49], 0, v[146:147]
	v_add_f32_e32 v29, 1.0, v34
	global_store_dwordx4 v[48:49], v[36:39], off nt
	v_rcp_f32_e32 v29, v29
	v_cvt_pk_bf16_f32 v20, v20, v21
	v_mul_f32_e32 v21, v30, v28
	v_mul_f32_e32 v28, 0xbfb8aa3b, v24
	v_exp_f32_e32 v28, v28
	v_mul_f32_e32 v21, v21, v22
	v_mul_f32_e32 v22, v31, v29
	v_mul_f32_e32 v29, 0xbfb8aa3b, v25
	v_exp_f32_e32 v29, v29
	v_mul_f32_e32 v22, v22, v23
	v_add_f32_e32 v23, 1.0, v28
	v_rcp_f32_e32 v23, v23
	v_add_f32_e32 v28, 1.0, v29
	v_rcp_f32_e32 v28, v28
	v_cvt_pk_bf16_f32 v21, v21, v22
	v_mul_f32_e32 v22, v24, v23
	v_mul_f32_e32 v23, 0xbfb8aa3b, v26
	v_exp_f32_e32 v23, v23
	v_mul_f32_e32 v24, 0xbfb8aa3b, v27
	v_exp_f32_e32 v24, v24
	v_mul_f32_e32 v16, v22, v16
	v_mul_f32_e32 v22, v25, v28
	v_mul_f32_e32 v17, v22, v17
	v_add_f32_e32 v22, 1.0, v23
	v_rcp_f32_e32 v23, v22
	v_add_f32_e32 v22, 1.0, v24
	v_rcp_f32_e32 v24, v22
	v_cvt_pk_bf16_f32 v22, v16, v17
	v_mul_f32_e32 v16, v26, v23
	v_mul_f32_e32 v16, v16, v18
	v_mul_f32_e32 v17, v27, v24
	v_mul_f32_e32 v17, v17, v19
	v_cvt_pk_bf16_f32 v23, v16, v17
	v_mul_f32_e32 v17, 0xbfb8aa3b, v12
	v_exp_f32_e32 v18, v17
	v_mul_f32_e32 v17, 0xbfb8aa3b, v13
	v_exp_f32_e32 v19, v17
	v_add_u32_e32 v32, 0xa0, v154
	v_add_f32_e32 v18, 1.0, v18
	v_rcp_f32_e32 v18, v18
	v_add_f32_e32 v19, 1.0, v19
	v_rcp_f32_e32 v19, v19
	v_mad_i64_i32 v[32:33], s[38:39], v32, s50, v[144:145]
	v_mul_f32_e32 v12, v12, v18
	v_mul_f32_e32 v4, v12, v4
	v_mul_f32_e32 v12, v13, v19
	v_mul_f32_e32 v13, 0xbfb8aa3b, v14
	v_exp_f32_e32 v13, v13
	v_mul_f32_e32 v18, 0xbfb8aa3b, v15
	v_exp_f32_e32 v18, v18
	v_mul_f32_e32 v5, v12, v5
	v_add_f32_e32 v12, 1.0, v13
	v_rcp_f32_e32 v12, v12
	v_lshl_add_u64 v[32:33], v[32:33], 0, v[146:147]
	v_add_f32_e32 v13, 1.0, v18
	global_store_dwordx4 v[32:33], v[20:23], off nt
	v_rcp_f32_e32 v13, v13
	v_cvt_pk_bf16_f32 v4, v4, v5
	v_mul_f32_e32 v5, v14, v12
	v_mul_f32_e32 v12, 0xbfb8aa3b, v8
	v_exp_f32_e32 v12, v12
	v_mul_f32_e32 v5, v5, v6
	v_mul_f32_e32 v6, v15, v13
	v_mul_f32_e32 v13, 0xbfb8aa3b, v9
	v_exp_f32_e32 v13, v13
	v_mul_f32_e32 v6, v6, v7
	v_add_f32_e32 v7, 1.0, v12
	v_rcp_f32_e32 v7, v7
	v_add_f32_e32 v12, 1.0, v13
	v_rcp_f32_e32 v12, v12
	v_cvt_pk_bf16_f32 v5, v5, v6
	v_mul_f32_e32 v6, v8, v7
	v_mul_f32_e32 v7, 0xbfb8aa3b, v10
	v_exp_f32_e32 v7, v7
	v_mul_f32_e32 v8, 0xbfb8aa3b, v11
	v_exp_f32_e32 v8, v8
	v_mul_f32_e32 v0, v6, v0
	v_mul_f32_e32 v6, v9, v12
	v_mul_f32_e32 v1, v6, v1
	v_add_f32_e32 v6, 1.0, v7
	v_rcp_f32_e32 v7, v6
	v_add_f32_e32 v6, 1.0, v8
	v_rcp_f32_e32 v8, v6
	v_add_u32_e32 v16, 0xb0, v154
	v_mad_i64_i32 v[16:17], s[38:39], v16, s50, v[144:145]
	v_lshl_add_u64 v[16:17], v[16:17], 0, v[146:147]
	v_cvt_pk_bf16_f32 v6, v0, v1
	v_mul_f32_e32 v0, v10, v7
	v_mul_f32_e32 v1, v11, v8
	s_andn2_b64 vcc, exec, s[2:3]
	s_mov_b64 s[2:3], -1
	v_mul_f32_e32 v0, v0, v2
	v_mul_f32_e32 v1, v1, v3
	v_cvt_pk_bf16_f32 v7, v0, v1
	global_store_dwordx4 v[16:17], v[4:7], off nt
	s_cbranch_vccnz .LBB0_601
	s_andn2_b64 vcc, exec, s[0:1]
	s_cbranch_vccnz .LBB0_600
	s_barrier
	s_branch .LBB0_600
.Lpeel_p7:
	ds_read_b128 v[144:147], v151
	ds_read_b128 v[154:157], v151 offset:1024
	ds_read_b128 v[158:161], v151 offset:2048
	ds_read_b128 v[162:165], v151 offset:3072
	ds_read_b128 v[166:169], v152
	ds_read_b128 v[170:173], v152 offset:1024
	ds_read_b128 v[176:179], v152 offset:2048
	ds_read_b128 v[180:183], v152 offset:3072
	s_add_u32 s33, s38, 0xfffc0080
	s_addc_u32 s40, s39, -1
	s_cmp_eq_u32 s56, 12
	s_cselect_b32 s43, s13, s40
	s_cselect_b32 s42, s52, s33
	s_cselect_b32 s41, s11, s55
	s_cselect_b32 s40, s53, s54
	ds_read_b128 v[184:187], v153
	ds_read_b128 v[188:191], v153 offset:1024
	ds_read_b128 v[192:195], v153 offset:2048
	ds_read_b128 v[196:199], v153 offset:3072
	ds_read_b128 v[200:203], v153 offset:4096
	ds_read_b128 v[204:207], v153 offset:5120
	ds_read_b128 v[208:211], v153 offset:6144
	ds_read_b128 v[212:215], v153 offset:7168
	s_waitcnt vmcnt(16)
	s_waitcnt lgkmcnt(0)
	s_barrier
	s_setprio 1
	s_waitcnt lgkmcnt(0)
	v_mfma_f32_16x16x32_bf16 v[124:127], v[144:147], v[184:187], 0
	v_mfma_f32_16x16x32_bf16 v[120:123], v[158:161], v[184:187], 0
	v_mfma_f32_16x16x32_bf16 v[108:111], v[144:147], v[192:195], 0
	v_mfma_f32_16x16x32_bf16 v[104:107], v[158:161], v[192:195], 0
	v_mfma_f32_16x16x32_bf16 v[92:95], v[144:147], v[200:203], 0
	v_mfma_f32_16x16x32_bf16 v[88:91], v[158:161], v[200:203], 0
	v_mfma_f32_16x16x32_bf16 v[76:79], v[144:147], v[208:211], 0
	v_mfma_f32_16x16x32_bf16 v[72:75], v[158:161], v[208:211], 0
	v_mfma_f32_16x16x32_bf16 v[124:127], v[154:157], v[188:191], v[124:127]
	v_mfma_f32_16x16x32_bf16 v[120:123], v[162:165], v[188:191], v[120:123]
	v_mfma_f32_16x16x32_bf16 v[108:111], v[154:157], v[196:199], v[108:111]
	v_mfma_f32_16x16x32_bf16 v[104:107], v[162:165], v[196:199], v[104:107]
	v_mfma_f32_16x16x32_bf16 v[92:95], v[154:157], v[204:207], v[92:95]
	v_mfma_f32_16x16x32_bf16 v[88:91], v[162:165], v[204:207], v[88:91]
	v_mfma_f32_16x16x32_bf16 v[76:79], v[154:157], v[212:215], v[76:79]
	v_mfma_f32_16x16x32_bf16 v[72:75], v[162:165], v[212:215], v[72:75]
	s_setprio 0
	s_setprio 1
	v_mfma_f32_16x16x32_bf16 v[116:119], v[166:169], v[184:187], 0
	v_mfma_f32_16x16x32_bf16 v[112:115], v[176:179], v[184:187], 0
	v_mfma_f32_16x16x32_bf16 v[100:103], v[166:169], v[192:195], 0
	v_mfma_f32_16x16x32_bf16 v[96:99], v[176:179], v[192:195], 0
	v_mfma_f32_16x16x32_bf16 v[84:87], v[166:169], v[200:203], 0
	v_mfma_f32_16x16x32_bf16 v[80:83], v[176:179], v[200:203], 0
	v_mfma_f32_16x16x32_bf16 v[68:71], v[166:169], v[208:211], 0
	v_mfma_f32_16x16x32_bf16 v[64:67], v[176:179], v[208:211], 0
	v_mfma_f32_16x16x32_bf16 v[116:119], v[170:173], v[188:191], v[116:119]
	v_mfma_f32_16x16x32_bf16 v[112:115], v[180:183], v[188:191], v[112:115]
	v_mfma_f32_16x16x32_bf16 v[100:103], v[170:173], v[196:199], v[100:103]
	v_mfma_f32_16x16x32_bf16 v[96:99], v[180:183], v[196:199], v[96:99]
	v_mfma_f32_16x16x32_bf16 v[84:87], v[170:173], v[204:207], v[84:87]
	v_mfma_f32_16x16x32_bf16 v[80:83], v[180:183], v[204:207], v[80:83]
	v_mfma_f32_16x16x32_bf16 v[68:71], v[170:173], v[212:215], v[68:71]
	v_mfma_f32_16x16x32_bf16 v[64:67], v[180:183], v[212:215], v[64:67]
	s_setprio 0
	s_barrier
; #define PG8_STAGE(bufoff, gbase, voff) do { _Pragma("unroll") for (int _i = 0; _i < 2; ++_i) \
;         __builtin_amdgcn_global_load_lds((const unsigned*)((const char*)(gbase) + (voff)[_i]), (PG8_LAS unsigned*)(lds + (bufoff) + ldsw + _i * 8192), 16, 0, 0); } while (0)
; #define PG8_LDA(dst, b, h) do { _Pragma("unroll") for (int m = 0; m < 4; ++m) _Pragma("unroll") for (int k = 0; k < 2; ++k) dst[m][k] = *(const PG8_LAS bf16x8*)(lds + PG8_SA(b, h) + aoff + m * 2048 + k * 1024); } while (0)
; #define PG8_LDB(dst, b, h) do { _Pragma("unroll") for (int n = 0; n < 2; ++n) _Pragma("unroll") for (int k = 0; k < 2; ++k) dst[n][k] = *(const PG8_LAS bf16x8*)(lds + PG8_SB(b, h) + boff + n * 2048 + k * 1024); } while (0)
; #define PG8_MMA(ai, bj, At, Bt) do { __builtin_amdgcn_s_setprio(1); _Pragma("unroll") for (int m = 0; m < 4; ++m) _Pragma("unroll") for (int n = 0; n < 2; ++n) _Pragma("unroll") for (int k = 0; k < 2; ++k) \
;         acc[ai][bj][m][n] = __builtin_amdgcn_mfma_f32_16x16x32_bf16(Bt[n][k], At[m][k], acc[ai][bj][m][n], 0, 0, 0); __builtin_amdgcn_s_setprio(0); } while (0)
; #define PG8_WAIT_V(n) asm volatile("s_waitcnt vmcnt(" #n ")" ::: "memory")
; #define PG8_WAIT_L(n) asm volatile("s_waitcnt lgkmcnt(" #n ")" ::: "memory")
; #define PG8_BAR __builtin_amdgcn_s_barrier()
; #define PG8_SCHED __builtin_amdgcn_sched_barrier(0)
; template <class Epi, class Sched, bool ALIGN_EPI = false, bool SP2 = false>
; __device__ __forceinline__ void gemm_phase(PG8_LAS unsigned char* lds, const Gemm g, const Sched& S, const Epi& E) {
;     ...
;             PG8_LDA(At, 0, 1); PG8_STAGE(PG8_SB(0, 0), b2, voffB); PG8_STAGE(PG8_SB(0, 1), b2 + hstepB, voffB); PG8_STAGE(PG8_SA(0, 0), a2, voffA);
;             PG8_WAIT_V(8); PG8_WAIT_L(0); PG8_BAR; PG8_MMA(1, 0, At, B0); PG8_MMA(1, 1, At, B1); PG8_BAR; PG8_SCHED;
;             PG8_LDB(B0, 1, 0); PG8_LDB(B1, 1, 1); PG8_SCHED; PG8_LDA(At, 1, 0); PG8_STAGE(PG8_SA(0, 1), a2 + hstepA, voffA);
;             PG8_WAIT_V(8); PG8_WAIT_L(0); PG8_BAR; PG8_MMA(0, 0, At, B0); PG8_MMA(0, 1, At, B1); PG8_BAR; PG8_SCHED;
	s_add_i32 s33, s48, s22
	v_lshl_add_u64 v[216:217], s[40:41], 0, v[132:133]
	s_mov_b32 m0, s33
	ds_read_b128 v[184:187], v153 offset:16384
	ds_read_b128 v[188:191], v153 offset:17408
	ds_read_b128 v[192:195], v153 offset:18432
	ds_read_b128 v[196:199], v153 offset:19456
	ds_read_b128 v[200:203], v153 offset:20480
	ds_read_b128 v[204:207], v153 offset:21504
	ds_read_b128 v[208:211], v153 offset:22528
	ds_read_b128 v[212:215], v153 offset:23552
	global_load_lds_dwordx4 v[216:217], off
	s_add_i32 m0, s33, 0x2000
	s_add_u32 s58, s40, 0x40000
	v_lshl_add_u64 v[218:219], s[40:41], 0, v[128:129]
	s_addc_u32 s59, s41, 0
	s_add_i32 s33, s49, s22
	global_load_lds_dwordx4 v[218:219], off
	v_lshl_add_u64 v[220:221], s[58:59], 0, v[132:133]
	s_mov_b32 m0, s33
	v_lshl_add_u64 v[222:223], s[42:43], 0, v[130:131]
	global_load_lds_dwordx4 v[220:221], off
	v_lshl_add_u64 v[220:221], s[58:59], 0, v[128:129]
	s_add_i32 m0, s33, 0x2000
	s_nop 0
	global_load_lds_dwordx4 v[220:221], off
	v_lshl_add_u64 v[220:221], s[42:43], 0, v[134:135]
	s_mov_b32 m0, s29
	s_nop 0
	global_load_lds_dwordx4 v[220:221], off
	s_mov_b32 m0, s30
	s_nop 0
	global_load_lds_dwordx4 v[222:223], off
	s_waitcnt vmcnt(16)
	s_waitcnt lgkmcnt(0)
	s_barrier
	s_setprio 1
	s_waitcnt lgkmcnt(0)
	v_mfma_f32_16x16x32_bf16 v[60:63], v[144:147], v[184:187], 0
	v_mfma_f32_16x16x32_bf16 v[56:59], v[158:161], v[184:187], 0
	v_mfma_f32_16x16x32_bf16 v[44:47], v[144:147], v[192:195], 0
	v_mfma_f32_16x16x32_bf16 v[40:43], v[158:161], v[192:195], 0
	v_mfma_f32_16x16x32_bf16 v[28:31], v[144:147], v[200:203], 0
	v_mfma_f32_16x16x32_bf16 v[24:27], v[158:161], v[200:203], 0
	v_mfma_f32_16x16x32_bf16 v[12:15], v[144:147], v[208:211], 0
	v_mfma_f32_16x16x32_bf16 v[8:11], v[158:161], v[208:211], 0
	v_mfma_f32_16x16x32_bf16 v[60:63], v[154:157], v[188:191], v[60:63]
	v_mfma_f32_16x16x32_bf16 v[56:59], v[162:165], v[188:191], v[56:59]
	v_mfma_f32_16x16x32_bf16 v[44:47], v[154:157], v[196:199], v[44:47]
	v_mfma_f32_16x16x32_bf16 v[40:43], v[162:165], v[196:199], v[40:43]
	v_mfma_f32_16x16x32_bf16 v[28:31], v[154:157], v[204:207], v[28:31]
	v_mfma_f32_16x16x32_bf16 v[24:27], v[162:165], v[204:207], v[24:27]
	v_mfma_f32_16x16x32_bf16 v[12:15], v[154:157], v[212:215], v[12:15]
	v_mfma_f32_16x16x32_bf16 v[8:11], v[162:165], v[212:215], v[8:11]
	s_setprio 0
	s_setprio 1
	v_mfma_f32_16x16x32_bf16 v[52:55], v[166:169], v[184:187], 0
	v_mfma_f32_16x16x32_bf16 v[48:51], v[176:179], v[184:187], 0
	v_mfma_f32_16x16x32_bf16 v[36:39], v[166:169], v[192:195], 0
	v_mfma_f32_16x16x32_bf16 v[32:35], v[176:179], v[192:195], 0
	v_mfma_f32_16x16x32_bf16 v[20:23], v[166:169], v[200:203], 0
	v_mfma_f32_16x16x32_bf16 v[16:19], v[176:179], v[200:203], 0
	v_mfma_f32_16x16x32_bf16 v[4:7], v[166:169], v[208:211], 0
	v_mfma_f32_16x16x32_bf16 v[0:3], v[176:179], v[208:211], 0
	v_mfma_f32_16x16x32_bf16 v[52:55], v[170:173], v[188:191], v[52:55]
	v_mfma_f32_16x16x32_bf16 v[48:51], v[180:183], v[188:191], v[48:51]
	v_mfma_f32_16x16x32_bf16 v[36:39], v[170:173], v[196:199], v[36:39]
	v_mfma_f32_16x16x32_bf16 v[32:35], v[180:183], v[196:199], v[32:35]
	v_mfma_f32_16x16x32_bf16 v[20:23], v[170:173], v[204:207], v[20:23]
	v_mfma_f32_16x16x32_bf16 v[16:19], v[180:183], v[204:207], v[16:19]
	v_mfma_f32_16x16x32_bf16 v[4:7], v[170:173], v[212:215], v[4:7]
	v_mfma_f32_16x16x32_bf16 v[0:3], v[180:183], v[212:215], v[0:3]
	s_setprio 0
	s_barrier
	s_add_i32 s33, 0, 0x18000
	s_add_i32 s57, 0, 0x1c000
	v_add_u32_e32 v162, s33, v149
	v_add_u32_e32 v175, s57, v149
	ds_read_b128 v[144:147], v162
	ds_read_b128 v[154:157], v162 offset:1024
	ds_read_b128 v[158:161], v162 offset:2048
	ds_read_b128 v[162:165], v162 offset:3072
	ds_read_b128 v[166:169], v175
	ds_read_b128 v[170:173], v175 offset:1024
	ds_read_b128 v[176:179], v175 offset:2048
	ds_read_b128 v[180:183], v175 offset:3072
	s_add_u32 s42, s42, 0x40000
	s_addc_u32 s43, s43, 0
	s_mov_b32 m0, s31
	v_lshl_add_u64 v[224:225], s[42:43], 0, v[134:135]
	ds_read_b128 v[184:187], v153 offset:32768
	ds_read_b128 v[188:191], v153 offset:33792
	ds_read_b128 v[192:195], v153 offset:34816
	ds_read_b128 v[196:199], v153 offset:35840
	ds_read_b128 v[200:203], v153 offset:36864
	ds_read_b128 v[204:207], v153 offset:37888
	ds_read_b128 v[208:211], v153 offset:38912
	ds_read_b128 v[212:215], v153 offset:39936
	global_load_lds_dwordx4 v[224:225], off
	v_lshl_add_u64 v[224:225], s[42:43], 0, v[130:131]
	s_mov_b32 m0, s35
	s_nop 0
	global_load_lds_dwordx4 v[224:225], off
	s_waitcnt vmcnt(16)
	s_waitcnt lgkmcnt(0)
	s_barrier
; #define PG8_STAGE(bufoff, gbase, voff) do { _Pragma("unroll") for (int _i = 0; _i < 2; ++_i) \
;         __builtin_amdgcn_global_load_lds((const unsigned*)((const char*)(gbase) + (voff)[_i]), (PG8_LAS unsigned*)(lds + (bufoff) + ldsw + _i * 8192), 16, 0, 0); } while (0)
; #define PG8_LDA(dst, b, h) do { _Pragma("unroll") for (int m = 0; m < 4; ++m) _Pragma("unroll") for (int k = 0; k < 2; ++k) dst[m][k] = *(const PG8_LAS bf16x8*)(lds + PG8_SA(b, h) + aoff + m * 2048 + k * 1024); } while (0)
; #define PG8_MMA(ai, bj, At, Bt) do { __builtin_amdgcn_s_setprio(1); _Pragma("unroll") for (int m = 0; m < 4; ++m) _Pragma("unroll") for (int n = 0; n < 2; ++n) _Pragma("unroll") for (int k = 0; k < 2; ++k) \
;         acc[ai][bj][m][n] = __builtin_amdgcn_mfma_f32_16x16x32_bf16(Bt[n][k], At[m][k], acc[ai][bj][m][n], 0, 0, 0); __builtin_amdgcn_s_setprio(0); } while (0)
; #define PG8_WAIT_V(n) asm volatile("s_waitcnt vmcnt(" #n ")" ::: "memory")
; #define PG8_WAIT_L(n) asm volatile("s_waitcnt lgkmcnt(" #n ")" ::: "memory")
; #define PG8_BAR __builtin_amdgcn_s_barrier()
; #define PG8_SCHED __builtin_amdgcn_sched_barrier(0)
; template <class Epi, class Sched, bool ALIGN_EPI = false, bool SP2 = false>
; __device__ __forceinline__ void gemm_phase(PG8_LAS unsigned char* lds, const Gemm g, const Sched& S, const Epi& E) {
;     ...
;         for (int t = 0; t < nt; t += 2) {
;             const bool last = (t == nt - 2);
;             const char* a1 = cA + (size_t)(t + 1) * kstep;
;             const char* a2 = last ? nA : cA + (size_t)(t + 2) * kstep; const char* b2 = last ? nB : cB + (size_t)(t + 2) * kstep;
;     ...
;             PG8_WAIT_V(8); PG8_WAIT_L(0); PG8_BAR; PG8_MMA(0, 0, At, B0); PG8_MMA(0, 1, At, B1); PG8_BAR; PG8_SCHED;
;             PG8_LDA(At, 1, 1); PG8_STAGE(PG8_SB(1, 0), b3, voffB); PG8_STAGE(PG8_SB(1, 1), b3 + hstepB, voffB); PG8_STAGE(PG8_SA(1, 0), a3, voffA);
;             PG8_WAIT_V(8); PG8_WAIT_L(0); PG8_BAR; PG8_MMA(1, 0, At, B0); PG8_MMA(1, 1, At, B1); PG8_BAR; PG8_SCHED;
	s_setprio 1
	s_waitcnt lgkmcnt(0)
	v_mfma_f32_16x16x32_bf16 v[124:127], v[144:147], v[184:187], v[124:127]
	v_mfma_f32_16x16x32_bf16 v[120:123], v[158:161], v[184:187], v[120:123]
	v_mfma_f32_16x16x32_bf16 v[108:111], v[144:147], v[192:195], v[108:111]
	v_mfma_f32_16x16x32_bf16 v[104:107], v[158:161], v[192:195], v[104:107]
	v_mfma_f32_16x16x32_bf16 v[92:95], v[144:147], v[200:203], v[92:95]
	v_mfma_f32_16x16x32_bf16 v[88:91], v[158:161], v[200:203], v[88:91]
	v_mfma_f32_16x16x32_bf16 v[76:79], v[144:147], v[208:211], v[76:79]
	v_mfma_f32_16x16x32_bf16 v[72:75], v[158:161], v[208:211], v[72:75]
	v_mfma_f32_16x16x32_bf16 v[124:127], v[154:157], v[188:191], v[124:127]
	v_mfma_f32_16x16x32_bf16 v[120:123], v[162:165], v[188:191], v[120:123]
	v_mfma_f32_16x16x32_bf16 v[108:111], v[154:157], v[196:199], v[108:111]
	v_mfma_f32_16x16x32_bf16 v[104:107], v[162:165], v[196:199], v[104:107]
	v_mfma_f32_16x16x32_bf16 v[92:95], v[154:157], v[204:207], v[92:95]
	v_mfma_f32_16x16x32_bf16 v[88:91], v[162:165], v[204:207], v[88:91]
	v_mfma_f32_16x16x32_bf16 v[76:79], v[154:157], v[212:215], v[76:79]
	v_mfma_f32_16x16x32_bf16 v[72:75], v[162:165], v[212:215], v[72:75]
	s_setprio 0
	s_setprio 1
	v_mfma_f32_16x16x32_bf16 v[116:119], v[166:169], v[184:187], v[116:119]
	v_mfma_f32_16x16x32_bf16 v[112:115], v[176:179], v[184:187], v[112:115]
	v_mfma_f32_16x16x32_bf16 v[100:103], v[166:169], v[192:195], v[100:103]
	v_mfma_f32_16x16x32_bf16 v[96:99], v[176:179], v[192:195], v[96:99]
	v_mfma_f32_16x16x32_bf16 v[84:87], v[166:169], v[200:203], v[84:87]
	v_mfma_f32_16x16x32_bf16 v[80:83], v[176:179], v[200:203], v[80:83]
	v_mfma_f32_16x16x32_bf16 v[68:71], v[166:169], v[208:211], v[68:71]
	v_mfma_f32_16x16x32_bf16 v[64:67], v[176:179], v[208:211], v[64:67]
	v_mfma_f32_16x16x32_bf16 v[116:119], v[170:173], v[188:191], v[116:119]
	v_mfma_f32_16x16x32_bf16 v[112:115], v[180:183], v[188:191], v[112:115]
	v_mfma_f32_16x16x32_bf16 v[100:103], v[170:173], v[196:199], v[100:103]
	v_mfma_f32_16x16x32_bf16 v[96:99], v[180:183], v[196:199], v[96:99]
	v_mfma_f32_16x16x32_bf16 v[84:87], v[170:173], v[204:207], v[84:87]
	v_mfma_f32_16x16x32_bf16 v[80:83], v[180:183], v[204:207], v[80:83]
	v_mfma_f32_16x16x32_bf16 v[68:71], v[170:173], v[212:215], v[68:71]
	v_mfma_f32_16x16x32_bf16 v[64:67], v[180:183], v[212:215], v[64:67]
	s_setprio 0
	s_barrier
	s_add_i32 s33, s33, s22
	v_lshl_add_u64 v[216:217], v[216:217], 0, s[6:7]
	s_mov_b32 m0, s33
	ds_read_b128 v[184:187], v153 offset:49152
	ds_read_b128 v[188:191], v153 offset:50176
	ds_read_b128 v[192:195], v153 offset:51200
	ds_read_b128 v[196:199], v153 offset:52224
	ds_read_b128 v[200:203], v153 offset:53248
	ds_read_b128 v[204:207], v153 offset:54272
	ds_read_b128 v[208:211], v153 offset:55296
	ds_read_b128 v[212:215], v153 offset:56320
	global_load_lds_dwordx4 v[216:217], off
	s_add_i32 m0, s33, 0x2000
	s_add_u32 s40, s40, 0x40080
	v_lshl_add_u64 v[216:217], v[218:219], 0, s[6:7]
	s_addc_u32 s41, s41, 0
	s_add_i32 s33, s57, s22
	global_load_lds_dwordx4 v[216:217], off
	v_lshl_add_u64 v[216:217], s[40:41], 0, v[132:133]
	s_mov_b32 m0, s33
	s_nop 0
	global_load_lds_dwordx4 v[216:217], off
	v_lshl_add_u64 v[216:217], s[40:41], 0, v[128:129]
	s_add_i32 m0, s33, 0x2000
	s_nop 0
	global_load_lds_dwordx4 v[216:217], off
	v_lshl_add_u64 v[216:217], v[220:221], 0, s[6:7]
	s_mov_b32 m0, s44
	s_nop 0
	global_load_lds_dwordx4 v[216:217], off
	v_lshl_add_u64 v[216:217], v[222:223], 0, s[6:7]
	s_mov_b32 m0, s45
	s_nop 0
	global_load_lds_dwordx4 v[216:217], off
	s_waitcnt vmcnt(8)
	s_waitcnt lgkmcnt(0)
	s_barrier
	s_setprio 1
	s_waitcnt lgkmcnt(0)
	v_mfma_f32_16x16x32_bf16 v[60:63], v[144:147], v[184:187], v[60:63]
	v_mfma_f32_16x16x32_bf16 v[56:59], v[158:161], v[184:187], v[56:59]
	v_mfma_f32_16x16x32_bf16 v[44:47], v[144:147], v[192:195], v[44:47]
	v_mfma_f32_16x16x32_bf16 v[40:43], v[158:161], v[192:195], v[40:43]
	v_mfma_f32_16x16x32_bf16 v[28:31], v[144:147], v[200:203], v[28:31]
	v_mfma_f32_16x16x32_bf16 v[24:27], v[158:161], v[200:203], v[24:27]
	v_mfma_f32_16x16x32_bf16 v[12:15], v[144:147], v[208:211], v[12:15]
	v_mfma_f32_16x16x32_bf16 v[8:11], v[158:161], v[208:211], v[8:11]
	v_mfma_f32_16x16x32_bf16 v[60:63], v[154:157], v[188:191], v[60:63]
	v_mfma_f32_16x16x32_bf16 v[56:59], v[162:165], v[188:191], v[56:59]
	v_mfma_f32_16x16x32_bf16 v[44:47], v[154:157], v[196:199], v[44:47]
	v_mfma_f32_16x16x32_bf16 v[40:43], v[162:165], v[196:199], v[40:43]
	v_mfma_f32_16x16x32_bf16 v[28:31], v[154:157], v[204:207], v[28:31]
	v_mfma_f32_16x16x32_bf16 v[24:27], v[162:165], v[204:207], v[24:27]
	v_mfma_f32_16x16x32_bf16 v[12:15], v[154:157], v[212:215], v[12:15]
	v_mfma_f32_16x16x32_bf16 v[8:11], v[162:165], v[212:215], v[8:11]
	s_setprio 0
	s_setprio 1
	v_mfma_f32_16x16x32_bf16 v[52:55], v[166:169], v[184:187], v[52:55]
	v_mfma_f32_16x16x32_bf16 v[48:51], v[176:179], v[184:187], v[48:51]
	v_mfma_f32_16x16x32_bf16 v[36:39], v[166:169], v[192:195], v[36:39]
	v_mfma_f32_16x16x32_bf16 v[32:35], v[176:179], v[192:195], v[32:35]
	v_mfma_f32_16x16x32_bf16 v[20:23], v[166:169], v[200:203], v[20:23]
	v_mfma_f32_16x16x32_bf16 v[16:19], v[176:179], v[200:203], v[16:19]
	v_mfma_f32_16x16x32_bf16 v[4:7], v[166:169], v[208:211], v[4:7]
	v_mfma_f32_16x16x32_bf16 v[0:3], v[176:179], v[208:211], v[0:3]
	v_mfma_f32_16x16x32_bf16 v[52:55], v[170:173], v[188:191], v[52:55]
	v_mfma_f32_16x16x32_bf16 v[48:51], v[180:183], v[188:191], v[48:51]
	v_mfma_f32_16x16x32_bf16 v[36:39], v[170:173], v[196:199], v[36:39]
	v_mfma_f32_16x16x32_bf16 v[32:35], v[180:183], v[196:199], v[32:35]
	v_mfma_f32_16x16x32_bf16 v[20:23], v[170:173], v[204:207], v[20:23]
	v_mfma_f32_16x16x32_bf16 v[16:19], v[180:183], v[204:207], v[16:19]
	v_mfma_f32_16x16x32_bf16 v[4:7], v[170:173], v[212:215], v[4:7]
	v_mfma_f32_16x16x32_bf16 v[0:3], v[180:183], v[212:215], v[0:3]
	s_setprio 0
	s_barrier
	s_add_i32 s56, s56, 2
	s_add_u32 s38, s38, 0x100
	s_addc_u32 s39, s39, 0
	s_add_u32 s54, s54, 0x100
	s_addc_u32 s55, s55, 0
	s_cmp_gt_u32 s56, 13
	s_branch .LBB0_605
